# speedup vs baseline: 1.0073x; 1.0046x over previous
; __device__ __forceinline__ unsigned cvt_pk_bf16(float lo, float hi) { unsigned r; asm volatile("v_cvt_pk_bf16_f32 %0, %1, %2" : "=v"(r) : "v"(lo), "v"(hi)); return r; }
; __device__ __forceinline__ float sigmoidf_(float x) { return __builtin_amdgcn_rcpf(1.0f + __expf(-x)); }
;     __device__ __forceinline__ void operator()(const f32x4 (&acc)[2][2][4][2], const Unit& u, int wr, int wc, int fr, int fq) const {
;     ...
;         const int row0 = u.pm * BM + wr * 64 + fr, col0 = u.pn * HALF + wc * 32 + 8 * fq;
;         float rsv[2][4];
; #pragma unroll
;         for (int ai = 0; ai < 2; ++ai)
; #pragma unroll
;             for (int m = 0; m < 4; ++m) rsv[ai][m] = rs_lookup(tab, rt, u.pm, wr * 64 + fr + ai * HALF + m * 16);
; #pragma unroll
;         for (int ai = 0; ai < 2; ++ai)
; #pragma unroll
;             for (int m = 0; m < 4; ++m) { const int row = row0 + ai * HALF + m * 16; bf16_t* rowp = O + (size_t)row * ldc + col0;
;                 const float rs = rsv[ai][m];
;                 float r[8];
; #pragma unroll
;                 for (int n = 0; n < 2; ++n)
; #pragma unroll
;                     for (int j = 0; j < 4; ++j) { const float g = acc[ai][0][m][n][j] * rs, up = acc[ai][1][m][n][j] * rs; r[n * 4 + j] = g * sigmoidf_(g) * up; }
;                 u32x4 w; w.x = cvt_pk_bf16(r[0], r[1]); w.y = cvt_pk_bf16(r[2], r[3]); w.z = cvt_pk_bf16(r[4], r[5]); w.w = cvt_pk_bf16(r[6], r[7]);
;                 __builtin_nontemporal_store(w, (u32x4*)rowp); }
.LBB0_673:
	s_lshl_b32 s13, s20, 8
	v_mov_b32_e32 v138, v150
	v_mov_b32_e32 v140, v151
	s_add_i32 s13, s13, s62
	s_nop 7
	s_nop 7
	s_cmp_eq_u32 s20, s31
	v_add_u32_e32 v172, s13, v138
	s_movk_i32 s13, 0x300
	s_cselect_b32 s13, 0x200, s13
	s_cmp_lg_u32 s20, s38
	s_cselect_b32 s13, s13, 0x100
	s_cmp_lg_u32 s20, s39
	s_cselect_b32 s13, s13, 0
	s_lshl_b32 s13, s13, 2
	s_add_i32 s13, s13, s66
	v_lshl_add_u32 v138, v138, 2, s13
	ds_read2_b32 v[146:147], v138 offset1:16
	ds_read2_b32 v[144:145], v138 offset0:32 offset1:48
	ds_read2_b32 v[142:143], v138 offset0:128 offset1:144
	ds_read2_b32 v[138:139], v138 offset0:160 offset1:176
	s_waitcnt lgkmcnt(0)
	s_lshl_b32 s13, s21, 7
	s_or_b32 s13, s13, s63
	v_lshl_add_u32 v200, v140, 3, s13
	v_ashrrev_i32_e32 v201, 31, v200
	v_lshlrev_b64 v[200:201], 1, v[200:201]
	v_mov_b64_e32 v[202:203], s[8:9]
	s_movk_i32 s13, 0x2c00
	v_mad_i64_i32 v[204:205], s[20:21], v172, s13, v[202:203]
	s_andn2_b64 vcc, exec, s[0:1]
	s_mov_b64 s[20:21], -1
	s_mov_b32 s86, 0xbfb8aa3b
	s_mov_b32 s82, 0x2c000
	s_mov_b32 s83, 0
	s_mov_b32 s84, 0xdc000
	s_mov_b32 s85, 0
	v_lshl_add_u64 v[204:205], v[204:205], 0, v[200:201]
	v_pk_mul_f32 v[124:125], v[124:125], v[146:147] op_sel_hi:[1,0]
	v_pk_mul_f32 v[126:127], v[126:127], v[146:147] op_sel_hi:[1,0]
	v_pk_mul_f32 v[116:117], v[116:117], v[146:147] op_sel_hi:[1,0]
	v_pk_mul_f32 v[118:119], v[118:119], v[146:147] op_sel_hi:[1,0]
	v_pk_mul_f32 v[120:121], v[120:121], v[146:147] op_sel_hi:[1,0]
	v_pk_mul_f32 v[122:123], v[122:123], v[146:147] op_sel_hi:[1,0]
	v_pk_mul_f32 v[112:113], v[112:113], v[146:147] op_sel_hi:[1,0]
	v_pk_mul_f32 v[114:115], v[114:115], v[146:147] op_sel_hi:[1,0]
	v_pk_mul_f32 v[206:207], v[124:125], s[86:87] op_sel_hi:[1,0]
	v_pk_mul_f32 v[208:209], v[126:127], s[86:87] op_sel_hi:[1,0]
	v_pk_mul_f32 v[210:211], v[116:117], s[86:87] op_sel_hi:[1,0]
	v_pk_mul_f32 v[212:213], v[118:119], s[86:87] op_sel_hi:[1,0]
	v_exp_f32_e32 v206, v206
	v_exp_f32_e32 v207, v207
	v_exp_f32_e32 v208, v208
	v_exp_f32_e32 v209, v209
	v_exp_f32_e32 v210, v210
	v_exp_f32_e32 v211, v211
	v_exp_f32_e32 v212, v212
	v_exp_f32_e32 v213, v213
	v_pk_add_f32 v[206:207], v[206:207], 1.0 op_sel_hi:[1,0]
	v_pk_add_f32 v[208:209], v[208:209], 1.0 op_sel_hi:[1,0]
	v_pk_add_f32 v[210:211], v[210:211], 1.0 op_sel_hi:[1,0]
	v_pk_add_f32 v[212:213], v[212:213], 1.0 op_sel_hi:[1,0]
	v_rcp_f32_e32 v206, v206
	v_rcp_f32_e32 v207, v207
	v_rcp_f32_e32 v208, v208
	v_rcp_f32_e32 v209, v209
	v_rcp_f32_e32 v210, v210
	v_rcp_f32_e32 v211, v211
	v_rcp_f32_e32 v212, v212
	v_rcp_f32_e32 v213, v213
	v_pk_mul_f32 v[124:125], v[124:125], v[206:207]
	v_pk_mul_f32 v[126:127], v[126:127], v[208:209]
	v_pk_mul_f32 v[116:117], v[116:117], v[210:211]
	v_pk_mul_f32 v[118:119], v[118:119], v[212:213]
	v_pk_mul_f32 v[120:121], v[120:121], v[124:125]
	v_pk_mul_f32 v[122:123], v[122:123], v[126:127]
	v_pk_mul_f32 v[112:113], v[112:113], v[116:117]
	v_pk_mul_f32 v[114:115], v[114:115], v[118:119]
	v_cvt_pk_bf16_f32 v214, v120, v121
	v_cvt_pk_bf16_f32 v215, v122, v123
	v_cvt_pk_bf16_f32 v216, v112, v113
	v_cvt_pk_bf16_f32 v217, v114, v115
	global_store_dwordx4 v[204:205], v[214:217], off nt
	v_lshl_add_u64 v[222:223], v[204:205], 0, s[82:83]
	v_pk_mul_f32 v[108:109], v[108:109], v[146:147] op_sel:[0,1] op_sel_hi:[1,1]
	v_pk_mul_f32 v[110:111], v[110:111], v[146:147] op_sel:[0,1] op_sel_hi:[1,1]
	v_pk_mul_f32 v[100:101], v[100:101], v[146:147] op_sel:[0,1] op_sel_hi:[1,1]
	v_pk_mul_f32 v[102:103], v[102:103], v[146:147] op_sel:[0,1] op_sel_hi:[1,1]
	v_pk_mul_f32 v[104:105], v[104:105], v[146:147] op_sel:[0,1] op_sel_hi:[1,1]
	v_pk_mul_f32 v[106:107], v[106:107], v[146:147] op_sel:[0,1] op_sel_hi:[1,1]
	v_pk_mul_f32 v[96:97], v[96:97], v[146:147] op_sel:[0,1] op_sel_hi:[1,1]
	v_pk_mul_f32 v[98:99], v[98:99], v[146:147] op_sel:[0,1] op_sel_hi:[1,1]
	v_pk_mul_f32 v[206:207], v[108:109], s[86:87] op_sel_hi:[1,0]
	v_pk_mul_f32 v[208:209], v[110:111], s[86:87] op_sel_hi:[1,0]
	v_pk_mul_f32 v[210:211], v[100:101], s[86:87] op_sel_hi:[1,0]
	v_pk_mul_f32 v[212:213], v[102:103], s[86:87] op_sel_hi:[1,0]
	v_exp_f32_e32 v206, v206
	v_exp_f32_e32 v207, v207
	v_exp_f32_e32 v208, v208
	v_exp_f32_e32 v209, v209
	v_exp_f32_e32 v210, v210
	v_exp_f32_e32 v211, v211
	v_exp_f32_e32 v212, v212
	v_exp_f32_e32 v213, v213
	v_pk_add_f32 v[206:207], v[206:207], 1.0 op_sel_hi:[1,0]
	v_pk_add_f32 v[208:209], v[208:209], 1.0 op_sel_hi:[1,0]
	v_pk_add_f32 v[210:211], v[210:211], 1.0 op_sel_hi:[1,0]
	v_pk_add_f32 v[212:213], v[212:213], 1.0 op_sel_hi:[1,0]
	v_rcp_f32_e32 v206, v206
	v_rcp_f32_e32 v207, v207
	v_rcp_f32_e32 v208, v208
	v_rcp_f32_e32 v209, v209
	v_rcp_f32_e32 v210, v210
	v_rcp_f32_e32 v211, v211
	v_rcp_f32_e32 v212, v212
	v_rcp_f32_e32 v213, v213
	v_pk_mul_f32 v[108:109], v[108:109], v[206:207]
	v_pk_mul_f32 v[110:111], v[110:111], v[208:209]
	v_pk_mul_f32 v[100:101], v[100:101], v[210:211]
	v_pk_mul_f32 v[102:103], v[102:103], v[212:213]
	v_pk_mul_f32 v[104:105], v[104:105], v[108:109]
	v_pk_mul_f32 v[106:107], v[106:107], v[110:111]
	v_pk_mul_f32 v[96:97], v[96:97], v[100:101]
	v_pk_mul_f32 v[98:99], v[98:99], v[102:103]
	v_cvt_pk_bf16_f32 v218, v104, v105
	v_cvt_pk_bf16_f32 v219, v106, v107
	v_cvt_pk_bf16_f32 v220, v96, v97
	v_cvt_pk_bf16_f32 v221, v98, v99
	global_store_dwordx4 v[222:223], v[218:221], off nt
	v_lshl_add_u64 v[204:205], v[222:223], 0, s[82:83]
	v_pk_mul_f32 v[92:93], v[92:93], v[144:145] op_sel_hi:[1,0]
	v_pk_mul_f32 v[94:95], v[94:95], v[144:145] op_sel_hi:[1,0]
	v_pk_mul_f32 v[84:85], v[84:85], v[144:145] op_sel_hi:[1,0]
	v_pk_mul_f32 v[86:87], v[86:87], v[144:145] op_sel_hi:[1,0]
	v_pk_mul_f32 v[88:89], v[88:89], v[144:145] op_sel_hi:[1,0]
; __device__ __forceinline__ unsigned cvt_pk_bf16(float lo, float hi) { unsigned r; asm volatile("v_cvt_pk_bf16_f32 %0, %1, %2" : "=v"(r) : "v"(lo), "v"(hi)); return r; }
; __device__ __forceinline__ float sigmoidf_(float x) { return __builtin_amdgcn_rcpf(1.0f + __expf(-x)); }
;     __device__ __forceinline__ void operator()(const f32x4 (&acc)[2][2][4][2], const Unit& u, int wr, int wc, int fr, int fq) const {
;     ...
;             for (int m = 0; m < 4; ++m) { const int row = row0 + ai * HALF + m * 16; bf16_t* rowp = O + (size_t)row * ldc + col0;
;                 const float rs = rsv[ai][m];
;                 float r[8];
; #pragma unroll
;                 for (int n = 0; n < 2; ++n)
; #pragma unroll
;                     for (int j = 0; j < 4; ++j) { const float g = acc[ai][0][m][n][j] * rs, up = acc[ai][1][m][n][j] * rs; r[n * 4 + j] = g * sigmoidf_(g) * up; }
;                 u32x4 w; w.x = cvt_pk_bf16(r[0], r[1]); w.y = cvt_pk_bf16(r[2], r[3]); w.z = cvt_pk_bf16(r[4], r[5]); w.w = cvt_pk_bf16(r[6], r[7]);
;                 __builtin_nontemporal_store(w, (u32x4*)rowp); }
	v_pk_mul_f32 v[90:91], v[90:91], v[144:145] op_sel_hi:[1,0]
	v_pk_mul_f32 v[80:81], v[80:81], v[144:145] op_sel_hi:[1,0]
	v_pk_mul_f32 v[82:83], v[82:83], v[144:145] op_sel_hi:[1,0]
	v_pk_mul_f32 v[206:207], v[92:93], s[86:87] op_sel_hi:[1,0]
	v_pk_mul_f32 v[208:209], v[94:95], s[86:87] op_sel_hi:[1,0]
	v_pk_mul_f32 v[210:211], v[84:85], s[86:87] op_sel_hi:[1,0]
	v_pk_mul_f32 v[212:213], v[86:87], s[86:87] op_sel_hi:[1,0]
	v_exp_f32_e32 v206, v206
	v_exp_f32_e32 v207, v207
	v_exp_f32_e32 v208, v208
	v_exp_f32_e32 v209, v209
	v_exp_f32_e32 v210, v210
	v_exp_f32_e32 v211, v211
	v_exp_f32_e32 v212, v212
	v_exp_f32_e32 v213, v213
	v_pk_add_f32 v[206:207], v[206:207], 1.0 op_sel_hi:[1,0]
	v_pk_add_f32 v[208:209], v[208:209], 1.0 op_sel_hi:[1,0]
	v_pk_add_f32 v[210:211], v[210:211], 1.0 op_sel_hi:[1,0]
	v_pk_add_f32 v[212:213], v[212:213], 1.0 op_sel_hi:[1,0]
	v_rcp_f32_e32 v206, v206
	v_rcp_f32_e32 v207, v207
	v_rcp_f32_e32 v208, v208
	v_rcp_f32_e32 v209, v209
	v_rcp_f32_e32 v210, v210
	v_rcp_f32_e32 v211, v211
	v_rcp_f32_e32 v212, v212
	v_rcp_f32_e32 v213, v213
	v_pk_mul_f32 v[92:93], v[92:93], v[206:207]
	v_pk_mul_f32 v[94:95], v[94:95], v[208:209]
	v_pk_mul_f32 v[84:85], v[84:85], v[210:211]
	v_pk_mul_f32 v[86:87], v[86:87], v[212:213]
	v_pk_mul_f32 v[88:89], v[88:89], v[92:93]
	v_pk_mul_f32 v[90:91], v[90:91], v[94:95]
	v_pk_mul_f32 v[80:81], v[80:81], v[84:85]
	v_pk_mul_f32 v[82:83], v[82:83], v[86:87]
	v_cvt_pk_bf16_f32 v214, v88, v89
	v_cvt_pk_bf16_f32 v215, v90, v91
	v_cvt_pk_bf16_f32 v216, v80, v81
	v_cvt_pk_bf16_f32 v217, v82, v83
	global_store_dwordx4 v[204:205], v[214:217], off nt
	v_lshl_add_u64 v[222:223], v[204:205], 0, s[82:83]
	v_pk_mul_f32 v[76:77], v[76:77], v[144:145] op_sel:[0,1] op_sel_hi:[1,1]
	v_pk_mul_f32 v[78:79], v[78:79], v[144:145] op_sel:[0,1] op_sel_hi:[1,1]
	v_pk_mul_f32 v[68:69], v[68:69], v[144:145] op_sel:[0,1] op_sel_hi:[1,1]
	v_pk_mul_f32 v[70:71], v[70:71], v[144:145] op_sel:[0,1] op_sel_hi:[1,1]
	v_pk_mul_f32 v[72:73], v[72:73], v[144:145] op_sel:[0,1] op_sel_hi:[1,1]
	v_pk_mul_f32 v[74:75], v[74:75], v[144:145] op_sel:[0,1] op_sel_hi:[1,1]
	v_pk_mul_f32 v[64:65], v[64:65], v[144:145] op_sel:[0,1] op_sel_hi:[1,1]
	v_pk_mul_f32 v[66:67], v[66:67], v[144:145] op_sel:[0,1] op_sel_hi:[1,1]
	v_pk_mul_f32 v[206:207], v[76:77], s[86:87] op_sel_hi:[1,0]
	v_pk_mul_f32 v[208:209], v[78:79], s[86:87] op_sel_hi:[1,0]
	v_pk_mul_f32 v[210:211], v[68:69], s[86:87] op_sel_hi:[1,0]
	v_pk_mul_f32 v[212:213], v[70:71], s[86:87] op_sel_hi:[1,0]
	v_exp_f32_e32 v206, v206
	v_exp_f32_e32 v207, v207
	v_exp_f32_e32 v208, v208
	v_exp_f32_e32 v209, v209
	v_exp_f32_e32 v210, v210
	v_exp_f32_e32 v211, v211
	v_exp_f32_e32 v212, v212
	v_exp_f32_e32 v213, v213
	v_pk_add_f32 v[206:207], v[206:207], 1.0 op_sel_hi:[1,0]
	v_pk_add_f32 v[208:209], v[208:209], 1.0 op_sel_hi:[1,0]
	v_pk_add_f32 v[210:211], v[210:211], 1.0 op_sel_hi:[1,0]
	v_pk_add_f32 v[212:213], v[212:213], 1.0 op_sel_hi:[1,0]
	v_rcp_f32_e32 v206, v206
	v_rcp_f32_e32 v207, v207
	v_rcp_f32_e32 v208, v208
	v_rcp_f32_e32 v209, v209
	v_rcp_f32_e32 v210, v210
	v_rcp_f32_e32 v211, v211
	v_rcp_f32_e32 v212, v212
	v_rcp_f32_e32 v213, v213
	v_pk_mul_f32 v[76:77], v[76:77], v[206:207]
	v_pk_mul_f32 v[78:79], v[78:79], v[208:209]
	v_pk_mul_f32 v[68:69], v[68:69], v[210:211]
	v_pk_mul_f32 v[70:71], v[70:71], v[212:213]
	v_pk_mul_f32 v[72:73], v[72:73], v[76:77]
	v_pk_mul_f32 v[74:75], v[74:75], v[78:79]
	v_pk_mul_f32 v[64:65], v[64:65], v[68:69]
	v_pk_mul_f32 v[66:67], v[66:67], v[70:71]
	v_cvt_pk_bf16_f32 v218, v72, v73
	v_cvt_pk_bf16_f32 v219, v74, v75
	v_cvt_pk_bf16_f32 v220, v64, v65
	v_cvt_pk_bf16_f32 v221, v66, v67
	global_store_dwordx4 v[222:223], v[218:221], off nt
	v_lshl_add_u64 v[204:205], v[222:223], 0, s[84:85]
	v_pk_mul_f32 v[60:61], v[60:61], v[142:143] op_sel_hi:[1,0]
	v_pk_mul_f32 v[62:63], v[62:63], v[142:143] op_sel_hi:[1,0]
	v_pk_mul_f32 v[52:53], v[52:53], v[142:143] op_sel_hi:[1,0]
	v_pk_mul_f32 v[54:55], v[54:55], v[142:143] op_sel_hi:[1,0]
	v_pk_mul_f32 v[56:57], v[56:57], v[142:143] op_sel_hi:[1,0]
	v_pk_mul_f32 v[58:59], v[58:59], v[142:143] op_sel_hi:[1,0]
	v_pk_mul_f32 v[48:49], v[48:49], v[142:143] op_sel_hi:[1,0]
	v_pk_mul_f32 v[50:51], v[50:51], v[142:143] op_sel_hi:[1,0]
	v_pk_mul_f32 v[206:207], v[60:61], s[86:87] op_sel_hi:[1,0]
	v_pk_mul_f32 v[208:209], v[62:63], s[86:87] op_sel_hi:[1,0]
	v_pk_mul_f32 v[210:211], v[52:53], s[86:87] op_sel_hi:[1,0]
	v_pk_mul_f32 v[212:213], v[54:55], s[86:87] op_sel_hi:[1,0]
	v_exp_f32_e32 v206, v206
	v_exp_f32_e32 v207, v207
	v_exp_f32_e32 v208, v208
	v_exp_f32_e32 v209, v209
	v_exp_f32_e32 v210, v210
	v_exp_f32_e32 v211, v211
	v_exp_f32_e32 v212, v212
	v_exp_f32_e32 v213, v213
	v_pk_add_f32 v[206:207], v[206:207], 1.0 op_sel_hi:[1,0]
	v_pk_add_f32 v[208:209], v[208:209], 1.0 op_sel_hi:[1,0]
	v_pk_add_f32 v[210:211], v[210:211], 1.0 op_sel_hi:[1,0]
	v_pk_add_f32 v[212:213], v[212:213], 1.0 op_sel_hi:[1,0]
	v_rcp_f32_e32 v206, v206
	v_rcp_f32_e32 v207, v207
	v_rcp_f32_e32 v208, v208
	v_rcp_f32_e32 v209, v209
	v_rcp_f32_e32 v210, v210
	v_rcp_f32_e32 v211, v211
	v_rcp_f32_e32 v212, v212
	v_rcp_f32_e32 v213, v213
	v_pk_mul_f32 v[60:61], v[60:61], v[206:207]
	v_pk_mul_f32 v[62:63], v[62:63], v[208:209]
	v_pk_mul_f32 v[52:53], v[52:53], v[210:211]
	v_pk_mul_f32 v[54:55], v[54:55], v[212:213]
	v_pk_mul_f32 v[56:57], v[56:57], v[60:61]
	v_pk_mul_f32 v[58:59], v[58:59], v[62:63]
	v_pk_mul_f32 v[48:49], v[48:49], v[52:53]
	v_pk_mul_f32 v[50:51], v[50:51], v[54:55]
	v_cvt_pk_bf16_f32 v214, v56, v57
	v_cvt_pk_bf16_f32 v215, v58, v59
	v_cvt_pk_bf16_f32 v216, v48, v49
	v_cvt_pk_bf16_f32 v217, v50, v51
	global_store_dwordx4 v[204:205], v[214:217], off nt
; __device__ __forceinline__ unsigned cvt_pk_bf16(float lo, float hi) { unsigned r; asm volatile("v_cvt_pk_bf16_f32 %0, %1, %2" : "=v"(r) : "v"(lo), "v"(hi)); return r; }
; __device__ __forceinline__ float sigmoidf_(float x) { return __builtin_amdgcn_rcpf(1.0f + __expf(-x)); }
; #define PG8_BAR __builtin_amdgcn_s_barrier()
; #define a (*get_args())
;     __device__ __forceinline__ void operator()(const f32x4 (&acc)[2][2][4][2], const Unit& u, int wr, int wc, int fr, int fq) const {
;     ...
;             for (int m = 0; m < 4; ++m) { const int row = row0 + ai * HALF + m * 16; bf16_t* rowp = O + (size_t)row * ldc + col0;
;                 const float rs = rsv[ai][m];
;                 float r[8];
; #pragma unroll
;                 for (int n = 0; n < 2; ++n)
; #pragma unroll
;                     for (int j = 0; j < 4; ++j) { const float g = acc[ai][0][m][n][j] * rs, up = acc[ai][1][m][n][j] * rs; r[n * 4 + j] = g * sigmoidf_(g) * up; }
;                 u32x4 w; w.x = cvt_pk_bf16(r[0], r[1]); w.y = cvt_pk_bf16(r[2], r[3]); w.z = cvt_pk_bf16(r[4], r[5]); w.w = cvt_pk_bf16(r[6], r[7]);
;                 __builtin_nontemporal_store(w, (u32x4*)rowp); }
;     }
; template <class Epi, class Sched>
; __device__ __forceinline__ void gemm_phase(const int tid, LAS unsigned char* lds, const Gemm g, const Sched& S, const Epi& E) {
;     ...
;         if (!has_next) break;
; #pragma unroll
;         for (int a = 0; a < 2; ++a)
; #pragma unroll
;             for (int b = 0; b < 2; ++b)
; #pragma unroll
;                 for (int m = 0; m < 4; ++m)
; #pragma unroll
;                     for (int n = 0; n < 2; ++n) acc[a][b][m][n] = (f32x4){0.f, 0.f, 0.f, 0.f};
;         cur = nxt; cA = nA; cB = nB; ++ui;
;         if (wr == 1) PG8_BAR;
	v_lshl_add_u64 v[222:223], v[204:205], 0, s[82:83]
	v_pk_mul_f32 v[44:45], v[44:45], v[142:143] op_sel:[0,1] op_sel_hi:[1,1]
	v_pk_mul_f32 v[46:47], v[46:47], v[142:143] op_sel:[0,1] op_sel_hi:[1,1]
	v_pk_mul_f32 v[36:37], v[36:37], v[142:143] op_sel:[0,1] op_sel_hi:[1,1]
	v_pk_mul_f32 v[38:39], v[38:39], v[142:143] op_sel:[0,1] op_sel_hi:[1,1]
	v_pk_mul_f32 v[40:41], v[40:41], v[142:143] op_sel:[0,1] op_sel_hi:[1,1]
	v_pk_mul_f32 v[42:43], v[42:43], v[142:143] op_sel:[0,1] op_sel_hi:[1,1]
	v_pk_mul_f32 v[32:33], v[32:33], v[142:143] op_sel:[0,1] op_sel_hi:[1,1]
	v_pk_mul_f32 v[34:35], v[34:35], v[142:143] op_sel:[0,1] op_sel_hi:[1,1]
	v_pk_mul_f32 v[206:207], v[44:45], s[86:87] op_sel_hi:[1,0]
	v_pk_mul_f32 v[208:209], v[46:47], s[86:87] op_sel_hi:[1,0]
	v_pk_mul_f32 v[210:211], v[36:37], s[86:87] op_sel_hi:[1,0]
	v_pk_mul_f32 v[212:213], v[38:39], s[86:87] op_sel_hi:[1,0]
	v_exp_f32_e32 v206, v206
	v_exp_f32_e32 v207, v207
	v_exp_f32_e32 v208, v208
	v_exp_f32_e32 v209, v209
	v_exp_f32_e32 v210, v210
	v_exp_f32_e32 v211, v211
	v_exp_f32_e32 v212, v212
	v_exp_f32_e32 v213, v213
	v_pk_add_f32 v[206:207], v[206:207], 1.0 op_sel_hi:[1,0]
	v_pk_add_f32 v[208:209], v[208:209], 1.0 op_sel_hi:[1,0]
	v_pk_add_f32 v[210:211], v[210:211], 1.0 op_sel_hi:[1,0]
	v_pk_add_f32 v[212:213], v[212:213], 1.0 op_sel_hi:[1,0]
	v_rcp_f32_e32 v206, v206
	v_rcp_f32_e32 v207, v207
	v_rcp_f32_e32 v208, v208
	v_rcp_f32_e32 v209, v209
	v_rcp_f32_e32 v210, v210
	v_rcp_f32_e32 v211, v211
	v_rcp_f32_e32 v212, v212
	v_rcp_f32_e32 v213, v213
	v_pk_mul_f32 v[44:45], v[44:45], v[206:207]
	v_pk_mul_f32 v[46:47], v[46:47], v[208:209]
	v_pk_mul_f32 v[36:37], v[36:37], v[210:211]
	v_pk_mul_f32 v[38:39], v[38:39], v[212:213]
	v_pk_mul_f32 v[40:41], v[40:41], v[44:45]
	v_pk_mul_f32 v[42:43], v[42:43], v[46:47]
	v_pk_mul_f32 v[32:33], v[32:33], v[36:37]
	v_pk_mul_f32 v[34:35], v[34:35], v[38:39]
	v_cvt_pk_bf16_f32 v218, v40, v41
	v_cvt_pk_bf16_f32 v219, v42, v43
	v_cvt_pk_bf16_f32 v220, v32, v33
	v_cvt_pk_bf16_f32 v221, v34, v35
	global_store_dwordx4 v[222:223], v[218:221], off nt
	v_lshl_add_u64 v[204:205], v[222:223], 0, s[82:83]
	v_pk_mul_f32 v[28:29], v[28:29], v[138:139] op_sel_hi:[1,0]
	v_pk_mul_f32 v[30:31], v[30:31], v[138:139] op_sel_hi:[1,0]
	v_pk_mul_f32 v[20:21], v[20:21], v[138:139] op_sel_hi:[1,0]
	v_pk_mul_f32 v[22:23], v[22:23], v[138:139] op_sel_hi:[1,0]
	v_pk_mul_f32 v[24:25], v[24:25], v[138:139] op_sel_hi:[1,0]
	v_pk_mul_f32 v[26:27], v[26:27], v[138:139] op_sel_hi:[1,0]
	v_pk_mul_f32 v[16:17], v[16:17], v[138:139] op_sel_hi:[1,0]
	v_pk_mul_f32 v[18:19], v[18:19], v[138:139] op_sel_hi:[1,0]
	v_pk_mul_f32 v[206:207], v[28:29], s[86:87] op_sel_hi:[1,0]
	v_pk_mul_f32 v[208:209], v[30:31], s[86:87] op_sel_hi:[1,0]
	v_pk_mul_f32 v[210:211], v[20:21], s[86:87] op_sel_hi:[1,0]
	v_pk_mul_f32 v[212:213], v[22:23], s[86:87] op_sel_hi:[1,0]
	v_exp_f32_e32 v206, v206
	v_exp_f32_e32 v207, v207
	v_exp_f32_e32 v208, v208
	v_exp_f32_e32 v209, v209
	v_exp_f32_e32 v210, v210
	v_exp_f32_e32 v211, v211
	v_exp_f32_e32 v212, v212
	v_exp_f32_e32 v213, v213
	v_pk_add_f32 v[206:207], v[206:207], 1.0 op_sel_hi:[1,0]
	v_pk_add_f32 v[208:209], v[208:209], 1.0 op_sel_hi:[1,0]
	v_pk_add_f32 v[210:211], v[210:211], 1.0 op_sel_hi:[1,0]
	v_pk_add_f32 v[212:213], v[212:213], 1.0 op_sel_hi:[1,0]
	v_rcp_f32_e32 v206, v206
	v_rcp_f32_e32 v207, v207
	v_rcp_f32_e32 v208, v208
	v_rcp_f32_e32 v209, v209
	v_rcp_f32_e32 v210, v210
	v_rcp_f32_e32 v211, v211
	v_rcp_f32_e32 v212, v212
	v_rcp_f32_e32 v213, v213
	v_pk_mul_f32 v[28:29], v[28:29], v[206:207]
	v_pk_mul_f32 v[30:31], v[30:31], v[208:209]
	v_pk_mul_f32 v[20:21], v[20:21], v[210:211]
	v_pk_mul_f32 v[22:23], v[22:23], v[212:213]
	v_pk_mul_f32 v[24:25], v[24:25], v[28:29]
	v_pk_mul_f32 v[26:27], v[26:27], v[30:31]
	v_pk_mul_f32 v[16:17], v[16:17], v[20:21]
	v_pk_mul_f32 v[18:19], v[18:19], v[22:23]
	v_cvt_pk_bf16_f32 v214, v24, v25
	v_cvt_pk_bf16_f32 v215, v26, v27
	v_cvt_pk_bf16_f32 v216, v16, v17
	v_cvt_pk_bf16_f32 v217, v18, v19
	global_store_dwordx4 v[204:205], v[214:217], off nt
	v_lshl_add_u64 v[222:223], v[204:205], 0, s[82:83]
	v_pk_mul_f32 v[12:13], v[12:13], v[138:139] op_sel:[0,1] op_sel_hi:[1,1]
	v_pk_mul_f32 v[14:15], v[14:15], v[138:139] op_sel:[0,1] op_sel_hi:[1,1]
	v_pk_mul_f32 v[4:5], v[4:5], v[138:139] op_sel:[0,1] op_sel_hi:[1,1]
	v_pk_mul_f32 v[6:7], v[6:7], v[138:139] op_sel:[0,1] op_sel_hi:[1,1]
	v_pk_mul_f32 v[8:9], v[8:9], v[138:139] op_sel:[0,1] op_sel_hi:[1,1]
	v_pk_mul_f32 v[10:11], v[10:11], v[138:139] op_sel:[0,1] op_sel_hi:[1,1]
	v_pk_mul_f32 v[0:1], v[0:1], v[138:139] op_sel:[0,1] op_sel_hi:[1,1]
	v_pk_mul_f32 v[2:3], v[2:3], v[138:139] op_sel:[0,1] op_sel_hi:[1,1]
	v_pk_mul_f32 v[206:207], v[12:13], s[86:87] op_sel_hi:[1,0]
	v_pk_mul_f32 v[208:209], v[14:15], s[86:87] op_sel_hi:[1,0]
	v_pk_mul_f32 v[210:211], v[4:5], s[86:87] op_sel_hi:[1,0]
	v_pk_mul_f32 v[212:213], v[6:7], s[86:87] op_sel_hi:[1,0]
	v_exp_f32_e32 v206, v206
	v_exp_f32_e32 v207, v207
	v_exp_f32_e32 v208, v208
	v_exp_f32_e32 v209, v209
	v_exp_f32_e32 v210, v210
	v_exp_f32_e32 v211, v211
	v_exp_f32_e32 v212, v212
	v_exp_f32_e32 v213, v213
	v_pk_add_f32 v[206:207], v[206:207], 1.0 op_sel_hi:[1,0]
	v_pk_add_f32 v[208:209], v[208:209], 1.0 op_sel_hi:[1,0]
	v_pk_add_f32 v[210:211], v[210:211], 1.0 op_sel_hi:[1,0]
	v_pk_add_f32 v[212:213], v[212:213], 1.0 op_sel_hi:[1,0]
	v_rcp_f32_e32 v206, v206
	v_rcp_f32_e32 v207, v207
	v_rcp_f32_e32 v208, v208
	v_rcp_f32_e32 v209, v209
	v_rcp_f32_e32 v210, v210
	v_rcp_f32_e32 v211, v211
	v_rcp_f32_e32 v212, v212
	v_rcp_f32_e32 v213, v213
	v_pk_mul_f32 v[12:13], v[12:13], v[206:207]
	v_pk_mul_f32 v[14:15], v[14:15], v[208:209]
	v_pk_mul_f32 v[4:5], v[4:5], v[210:211]
	v_pk_mul_f32 v[6:7], v[6:7], v[212:213]
	v_pk_mul_f32 v[8:9], v[8:9], v[12:13]
	v_pk_mul_f32 v[10:11], v[10:11], v[14:15]
	v_pk_mul_f32 v[0:1], v[0:1], v[4:5]
	v_pk_mul_f32 v[2:3], v[2:3], v[6:7]
	v_cvt_pk_bf16_f32 v218, v8, v9
	v_cvt_pk_bf16_f32 v219, v10, v11
	v_cvt_pk_bf16_f32 v220, v0, v1
	v_cvt_pk_bf16_f32 v221, v2, v3
	global_store_dwordx4 v[222:223], v[218:221], off nt
	s_cbranch_vccnz .LBB0_666
	s_andn2_b64 vcc, exec, s[6:7]
	s_cbranch_vccnz .LBB0_665
	s_barrier
	s_branch .LBB0_665
